# v120 plus one static s_setprio 1 for waves 4-7 before every GEMM K loop
# speedup vs baseline: 1.0038x; 1.0038x over previous
; #define GPTR(T, ptr) ((__attribute__((address_space(1))) T*)(ptr))
; __device__ __forceinline__ float frsq(float x) { return __builtin_amdgcn_rsqf(x); }
; __device__ __forceinline__ int ptid_(int wave) { int l_; asm volatile("v_mbcnt_lo_u32_b32 %0, -1, 0\n\tv_mbcnt_hi_u32_b32 %0, -1, %0" : "=v"(l_)); return (wave << 6) | l_; }
; #define STAGE_B(P, br, kt) do { const char* _gb = (const char*)(Bt + ((long)(br) * K + (long)(kt) * BK)); \
;     __builtin_amdgcn_global_load_lds((const unsigned*)(_gb + bofl0), (unsigned*)((char*)(P) + gtid_ * 16), 16, 0, 0); \
;     __builtin_amdgcn_global_load_lds((const unsigned*)(_gb + (long)K * 128 + bofl0), (unsigned*)((char*)(P) + gtid_ * 16 + 8192), 16, 0, 0); } while (0)
; #define BAR __builtin_amdgcn_s_barrier()
; template <int EPI>
; __device__ __forceinline__ void gemm_tile(const GemmArgs& g, int brow, int bcol, int parity, bool first, bool nvalid, int nbrow, int nbcol) {
;     ...
;   int gtid_ = ptid_(g.tid);
;   const int wid = gtid_ >> 6, lane = gtid_ & 63, wr = wid >> 2, wc = wid & 3, fr = lane & 15, fq = lane >> 4;
;   unsigned aofl0, bofl0;
;   { int _r, _c; stage_rc(gtid_ * 16, _r, _c); aofl0 = (unsigned)(_r * lda + _c) * 2u; bofl0 = (unsigned)(_r * K + _c) * 2u; }
;   f32x4 acc[2][2][4][2] = {};
;   bf16x8 At[4][2], B0[2][2], B1[2][2];
;   const int nt = K / BK;
;   float* rstd_s = (float*)(smem + 153600) + (parity & 1) * 256;
;   if (first) {
;     WAIT_V(0);
;     __syncthreads();
;     STAGE_B(SB(0, 0), bcol, 0); STAGE_A(SA(0, 0), brow, 0);
;     STAGE_B(SB(0, 1), bcol + HALF, 0); STAGE_A(SA(0, 1), brow + HALF, 0);
;   }
;   f32x4 ra0, ra1, ra2, ra3;
;   if constexpr (EPI != EPI_RES) {
;     if (gtid_ < 256) {
;       const __attribute__((address_space(1))) f32x4* pp = GPTR(const f32x4, g.rowss + (long)(brow + gtid_) * 16);
;       ra0 = pp[0]; ra1 = pp[1]; ra2 = pp[2]; ra3 = pp[3];
;     }
;   }
;   if (wr == 1) BAR;
;   if (first) { WAIT_V(4); } else { WAIT_V(0); }
;   BAR;
;   if constexpr (EPI != EPI_RES) {
;     if (gtid_ < 256) {
;       float s = ((ra0[0] + ra0[1]) + (ra0[2] + ra0[3])) + ((ra1[0] + ra1[1]) + (ra1[2] + ra1[3])) + ((ra2[0] + ra2[1]) + (ra2[2] + ra2[3])) + ((ra3[0] + ra3[1]) + (ra3[2] + ra3[3]));
;       rstd_s[gtid_] = frsq(s * (1.0f / 1024.0f) + 1e-6f);
;     }
;   }
;   STAGE_B(SB(1, 0), bcol, 1); STAGE_A(SA(1, 0), brow, 1); STAGE_B(SB(1, 1), bcol + HALF, 1);
;   WAIT_V(6); BAR;
.LBB0_89:
	s_or_b64 exec, exec, s[14:15]
	s_ashr_i32 s13, s12, 31
	s_lshl_b64 s[26:27], s[12:13], 11
	s_add_u32 s0, s22, s26
	v_readlane_b32 s13, v254, 8
	s_addc_u32 s1, s23, s27
	s_waitcnt vmcnt(0)
	v_lshl_add_u64 v[2:3], s[0:1], 0, v[0:1]
	v_add_u32_e32 v150, s13, v142
	s_mov_b64 s[14:15], 0x80
	v_readfirstlane_b32 s0, v150
	v_add_u32_e32 v151, 0x2000, v150
	v_lshl_add_u64 v[4:5], v[2:3], 0, s[14:15]
	s_mov_b32 m0, s0
	v_readfirstlane_b32 s0, v151
	s_ashr_i32 s39, s38, 31
	global_load_lds_dwordx4 v[4:5], off
	s_mov_b32 m0, s0
	s_lshl_b64 s[0:1], s[38:39], 11
	s_mov_b64 s[36:37], 0x20080
	s_add_u32 s0, s80, s0
	v_lshl_add_u64 v[2:3], v[2:3], 0, s[36:37]
	s_addc_u32 s1, s81, s1
	v_add_u32_e32 v152, 0x8000, v137
	global_load_lds_dwordx4 v[2:3], off
	v_lshl_add_u64 v[2:3], s[0:1], 0, v[0:1]
	v_readfirstlane_b32 s0, v152
	v_add_u32_e32 v153, 0xa000, v137
	v_lshl_add_u64 v[4:5], v[2:3], 0, s[14:15]
	s_mov_b32 m0, s0
	v_readfirstlane_b32 s0, v153
	global_load_lds_dwordx4 v[4:5], off
	s_mov_b32 m0, s0
	s_or_b32 s0, s12, 0x80
	s_ashr_i32 s1, s0, 31
	s_lshl_b64 s[0:1], s[0:1], 11
	s_add_u32 s0, s22, s0
	v_lshl_add_u64 v[2:3], v[2:3], 0, s[36:37]
	s_addc_u32 s1, s23, s1
	global_load_lds_dwordx4 v[2:3], off
	v_lshl_add_u64 v[2:3], s[0:1], 0, v[0:1]
	v_readlane_b32 s1, v254, 9
	v_lshl_add_u64 v[4:5], v[2:3], 0, s[14:15]
	v_lshl_add_u64 v[2:3], v[2:3], 0, s[36:37]
	v_add_u32_e32 v155, s1, v142
	v_add_u32_e32 v156, 0x2000, v155
	v_readfirstlane_b32 s0, v155
	s_mov_b32 m0, s0
	v_readfirstlane_b32 s0, v156
	global_load_lds_dwordx4 v[4:5], off
	s_mov_b32 m0, s0
	v_and_b32_e32 v139, 15, v132
	global_load_lds_dwordx4 v[2:3], off
	v_lshlrev_b32_e32 v5, 2, v132
	v_and_b32_e32 v2, 48, v132
	v_lshlrev_b32_e32 v4, 6, v139
	v_and_b32_e32 v5, 32, v5
	v_bitop3_b32 v4, v4, v5, v2 bitop3:0x36
	v_readlane_b32 s0, v254, 7
	v_lshlrev_b32_e32 v11, 6, v132
	v_add_u32_e32 v9, s1, v4
	v_add_u32_e32 v7, s0, v4
	s_movk_i32 s0, 0x3c0
	v_and_or_b32 v2, v11, s0, v2
	s_add_i32 s0, s2, s3
	v_xad_u32 v5, v2, v5, 0
	v_lshlrev_b32_e32 v2, 14, v18
	s_ashr_i32 s1, s0, 31
	s_add_i32 s14, 0, 0x10000
	v_and_b32_e32 v2, 0xffff8000, v2
	s_lshl_b64 s[0:1], s[0:1], 11
	v_ashrrev_i32_e32 v140, 6, v138
	v_lshl_add_u32 v2, v19, 11, v2
	v_and_b32_e32 v14, 1, v18
	s_add_u32 s0, s10, s0
	v_and_b32_e32 v141, 3, v140
	s_waitcnt vmcnt(6)
	v_lshlrev_b32_e32 v10, 13, v21
	v_lshl_or_b32 v2, v14, 6, v2
	s_addc_u32 s1, s11, s1
	v_lshlrev_b32_e32 v3, 12, v141
	v_add_u32_e32 v6, s14, v4
	v_add_u32_e32 v8, s13, v4
	v_add_u32_e32 v4, 0, v4
	v_or_b32_e32 v11, 0x800, v10
	v_or_b32_e32 v12, 0x1000, v10
	v_or_b32_e32 v13, 0x1800, v10
	v_lshl_add_u32 v130, v20, 1, v2
	s_add_u32 s12, s73, s26
	v_readlane_b32 s2, v255, 0
	v_mov_b32_e32 v2, 0
	v_lshlrev_b32_e32 v143, 6, v21
	v_mov_b32_e32 v131, v1
	s_addc_u32 s13, s2, s27
	s_mov_b32 s15, -2
	v_add_u32_e32 v157, v6, v3
	v_add_u32_e32 v147, v4, v10
	v_add_u32_e32 v146, v5, v11
	v_add_u32_e32 v145, v5, v12
	v_add_u32_e32 v144, v5, v13
	v_add_u32_e32 v154, v7, v3
	v_add_u32_e32 v149, v8, v3
	v_add_u32_e32 v148, v9, v3
	v_mov_b32_e32 v3, v2
	v_mov_b32_e32 v4, v2
	v_mov_b32_e32 v5, v2
	v_mov_b32_e32 v6, v2
	v_mov_b32_e32 v7, v2
	v_mov_b32_e32 v8, v2
	v_mov_b32_e32 v9, v2
	v_mov_b32_e32 v10, v2
	v_mov_b32_e32 v11, v2
	v_mov_b32_e32 v12, v2
	v_mov_b32_e32 v13, v2
	v_mov_b32_e32 v14, v2
	v_mov_b32_e32 v15, v2
	v_mov_b32_e32 v16, v2
	v_mov_b32_e32 v17, v2
	v_mov_b32_e32 v18, v2
	v_mov_b32_e32 v19, v2
	v_mov_b32_e32 v20, v2
	v_mov_b32_e32 v21, v2
	v_mov_b32_e32 v22, v2
	v_mov_b32_e32 v23, v2
	v_mov_b32_e32 v24, v2
	v_mov_b32_e32 v25, v2
	v_mov_b32_e32 v26, v2
	v_mov_b32_e32 v27, v2
	v_mov_b32_e32 v28, v2
	v_mov_b32_e32 v29, v2
	v_mov_b32_e32 v30, v2
	v_mov_b32_e32 v31, v2
	v_mov_b32_e32 v32, v2
	v_mov_b32_e32 v33, v2
	v_mov_b32_e32 v34, v2
	v_mov_b32_e32 v35, v2
	v_mov_b32_e32 v36, v2
	v_mov_b32_e32 v37, v2
	v_mov_b32_e32 v38, v2
	v_mov_b32_e32 v39, v2
	v_mov_b32_e32 v40, v2
	v_mov_b32_e32 v41, v2
	v_mov_b32_e32 v42, v2
	v_mov_b32_e32 v43, v2
	v_mov_b32_e32 v44, v2
	v_mov_b32_e32 v45, v2
	v_mov_b32_e32 v46, v2
	v_mov_b32_e32 v47, v2
	v_mov_b32_e32 v48, v2
	v_mov_b32_e32 v49, v2
	v_mov_b32_e32 v50, v2
	v_mov_b32_e32 v51, v2
	v_mov_b32_e32 v52, v2
	v_mov_b32_e32 v53, v2
	v_mov_b32_e32 v54, v2
	v_mov_b32_e32 v55, v2
	v_mov_b32_e32 v56, v2
	v_mov_b32_e32 v57, v2
	v_mov_b32_e32 v58, v2
	v_mov_b32_e32 v59, v2
	v_mov_b32_e32 v60, v2
	v_mov_b32_e32 v61, v2
	v_mov_b32_e32 v62, v2
	v_mov_b32_e32 v63, v2
	v_mov_b32_e32 v64, v2
	v_mov_b32_e32 v65, v2
	v_mov_b32_e32 v66, v2
	v_mov_b32_e32 v67, v2
	v_mov_b32_e32 v68, v2
	v_mov_b32_e32 v69, v2
	v_mov_b32_e32 v70, v2
	v_mov_b32_e32 v71, v2
	v_mov_b32_e32 v72, v2
	v_mov_b32_e32 v73, v2
	v_mov_b32_e32 v74, v2
	v_mov_b32_e32 v75, v2
	v_mov_b32_e32 v76, v2
	v_mov_b32_e32 v77, v2
	v_mov_b32_e32 v78, v2
	v_mov_b32_e32 v79, v2
	v_mov_b32_e32 v80, v2
	v_mov_b32_e32 v81, v2
	v_mov_b32_e32 v82, v2
	v_mov_b32_e32 v83, v2
	v_mov_b32_e32 v84, v2
	v_mov_b32_e32 v85, v2
	v_mov_b32_e32 v86, v2
	v_mov_b32_e32 v87, v2
	v_mov_b32_e32 v88, v2
	v_mov_b32_e32 v89, v2
	v_mov_b32_e32 v90, v2
	v_mov_b32_e32 v91, v2
	v_mov_b32_e32 v92, v2
	v_mov_b32_e32 v93, v2
	v_mov_b32_e32 v94, v2
	v_mov_b32_e32 v95, v2
	v_mov_b32_e32 v96, v2
	v_mov_b32_e32 v97, v2
	v_mov_b32_e32 v98, v2
	v_mov_b32_e32 v99, v2
	v_mov_b32_e32 v100, v2
	v_mov_b32_e32 v101, v2
	v_mov_b32_e32 v102, v2
	v_mov_b32_e32 v103, v2
	v_mov_b32_e32 v104, v2
	v_mov_b32_e32 v105, v2
	v_mov_b32_e32 v106, v2
	v_mov_b32_e32 v107, v2
	v_mov_b32_e32 v108, v2
	v_mov_b32_e32 v109, v2
	v_mov_b32_e32 v110, v2
	v_mov_b32_e32 v111, v2
	v_mov_b32_e32 v112, v2
	v_mov_b32_e32 v113, v2
	v_mov_b32_e32 v114, v2
	v_mov_b32_e32 v115, v2
	v_mov_b32_e32 v116, v2
	v_mov_b32_e32 v117, v2
	v_mov_b32_e32 v118, v2
	v_mov_b32_e32 v119, v2
	v_mov_b32_e32 v120, v2
	v_mov_b32_e32 v121, v2
	v_mov_b32_e32 v122, v2
	v_mov_b32_e32 v123, v2
	v_mov_b32_e32 v124, v2
	v_mov_b32_e32 v125, v2
	v_mov_b32_e32 v126, v2
	v_mov_b32_e32 v127, v2
	v_mov_b32_e32 v128, v2
	v_mov_b32_e32 v129, v2
	s_mov_b64 s[26:27], 0x8240080
	s_mov_b64 s[36:37], 0x8260080
	s_mov_b64 s[40:41], 0x8200100
	s_mov_b64 s[44:45], 0x8220100
	s_mov_b64 s[46:47], 0x8240100
	s_mov_b64 s[48:49], 0x8260100
	s_mov_b64 s[50:51], 0x8200180
	s_mov_b64 s[52:53], 0x8220180
	s_cmp_ge_u32 s33, 0x100
	s_cbranch_scc0 .Lprio_done_0
	s_setprio 1
.Lprio_done_0:
	s_barrier

; #define GPTR(T, ptr) ((__attribute__((address_space(1))) T*)(ptr))
; __device__ __forceinline__ float frsq(float x) { return __builtin_amdgcn_rsqf(x); }
; __device__ __forceinline__ int ptid_(int wave) { int l_; asm volatile("v_mbcnt_lo_u32_b32 %0, -1, 0\n\tv_mbcnt_hi_u32_b32 %0, -1, %0" : "=v"(l_)); return (wave << 6) | l_; }
; #define STAGE_B(P, br, kt) do { const char* _gb = (const char*)(Bt + ((long)(br) * K + (long)(kt) * BK)); \
;     __builtin_amdgcn_global_load_lds((const unsigned*)(_gb + bofl0), (unsigned*)((char*)(P) + gtid_ * 16), 16, 0, 0); \
;     __builtin_amdgcn_global_load_lds((const unsigned*)(_gb + (long)K * 128 + bofl0), (unsigned*)((char*)(P) + gtid_ * 16 + 8192), 16, 0, 0); } while (0)
; #define BAR __builtin_amdgcn_s_barrier()
; template <int EPI>
; __device__ __forceinline__ void gemm_tile(const GemmArgs& g, int brow, int bcol, int parity, bool first, bool nvalid, int nbrow, int nbcol) {
;     ...
;   int gtid_ = ptid_(g.tid);
;   const int wid = gtid_ >> 6, lane = gtid_ & 63, wr = wid >> 2, wc = wid & 3, fr = lane & 15, fq = lane >> 4;
;   unsigned aofl0, bofl0;
;   { int _r, _c; stage_rc(gtid_ * 16, _r, _c); aofl0 = (unsigned)(_r * lda + _c) * 2u; bofl0 = (unsigned)(_r * K + _c) * 2u; }
;   f32x4 acc[2][2][4][2] = {};
;   bf16x8 At[4][2], B0[2][2], B1[2][2];
;   const int nt = K / BK;
;   float* rstd_s = (float*)(smem + 153600) + (parity & 1) * 256;
;   if (first) {
;     WAIT_V(0);
;     __syncthreads();
;     STAGE_B(SB(0, 0), bcol, 0); STAGE_A(SA(0, 0), brow, 0);
;     STAGE_B(SB(0, 1), bcol + HALF, 0); STAGE_A(SA(0, 1), brow + HALF, 0);
;   }
;   f32x4 ra0, ra1, ra2, ra3;
;   if constexpr (EPI != EPI_RES) {
;     if (gtid_ < 256) {
;       const __attribute__((address_space(1))) f32x4* pp = GPTR(const f32x4, g.rowss + (long)(brow + gtid_) * 16);
;       ra0 = pp[0]; ra1 = pp[1]; ra2 = pp[2]; ra3 = pp[3];
;     }
;   }
;   if (wr == 1) BAR;
;   if (first) { WAIT_V(4); } else { WAIT_V(0); }
;   BAR;
;   if constexpr (EPI != EPI_RES) {
;     if (gtid_ < 256) {
;       float s = ((ra0[0] + ra0[1]) + (ra0[2] + ra0[3])) + ((ra1[0] + ra1[1]) + (ra1[2] + ra1[3])) + ((ra2[0] + ra2[1]) + (ra2[2] + ra2[3])) + ((ra3[0] + ra3[1]) + (ra3[2] + ra3[3]));
;       rstd_s[gtid_] = frsq(s * (1.0f / 1024.0f) + 1e-6f);
;     }
;   }
;   STAGE_B(SB(1, 0), bcol, 1); STAGE_A(SA(1, 0), brow, 1); STAGE_B(SB(1, 1), bcol + HALF, 1);
;   WAIT_V(6); BAR;
.LBB0_132:
	s_or_b64 exec, exec, s[12:13]
	s_ashr_i32 s39, s38, 31
	s_lshl_b64 s[0:1], s[38:39], 11
	s_add_u32 s0, s73, s0
	v_readlane_b32 s15, v255, 0
	v_readlane_b32 s22, v254, 8
	s_addc_u32 s1, s15, s1
	s_waitcnt vmcnt(0)
	v_lshl_add_u64 v[2:3], s[0:1], 0, v[0:1]
	v_add_u32_e32 v149, s22, v141
	s_mov_b64 s[24:25], 0x80
	v_readfirstlane_b32 s12, v149
	v_add_u32_e32 v151, 0x2000, v149
	v_lshl_add_u64 v[4:5], v[2:3], 0, s[24:25]
	s_mov_b32 m0, s12
	v_readfirstlane_b32 s12, v151
	s_ashr_i32 s41, s40, 31
	global_load_lds_dwordx4 v[4:5], off
	s_mov_b32 m0, s12
	s_lshl_b64 s[12:13], s[40:41], 11
	s_mov_b64 s[34:35], 0x20080
	s_add_u32 s12, s80, s12
	v_lshl_add_u64 v[2:3], v[2:3], 0, s[34:35]
	s_addc_u32 s13, s81, s13
	v_add_u32_e32 v152, 0x8000, v137
	global_load_lds_dwordx4 v[2:3], off
	v_lshl_add_u64 v[2:3], s[12:13], 0, v[0:1]
	v_readfirstlane_b32 s12, v152
	v_add_u32_e32 v153, 0xa000, v137
	v_lshl_add_u64 v[4:5], v[2:3], 0, s[24:25]
	s_mov_b32 m0, s12
	v_readfirstlane_b32 s12, v153
	global_load_lds_dwordx4 v[4:5], off
	s_mov_b32 m0, s12
	s_or_b32 s12, s38, 0x80
	s_ashr_i32 s13, s12, 31
	s_lshl_b64 s[12:13], s[12:13], 11
	s_add_u32 s12, s73, s12
	v_lshl_add_u64 v[2:3], v[2:3], 0, s[34:35]
	s_addc_u32 s13, s15, s13
	global_load_lds_dwordx4 v[2:3], off
	v_lshl_add_u64 v[2:3], s[12:13], 0, v[0:1]
	v_readlane_b32 s13, v254, 9
	v_lshl_add_u64 v[4:5], v[2:3], 0, s[24:25]
	v_lshl_add_u64 v[2:3], v[2:3], 0, s[34:35]
	v_add_u32_e32 v155, s13, v141
	v_add_u32_e32 v156, 0x2000, v155
	v_readfirstlane_b32 s12, v155
	s_mov_b32 m0, s12
	v_readfirstlane_b32 s12, v156
	global_load_lds_dwordx4 v[4:5], off
	s_mov_b32 m0, s12
	v_and_b32_e32 v150, 15, v132
	global_load_lds_dwordx4 v[2:3], off
	v_lshlrev_b32_e32 v5, 2, v132
	v_and_b32_e32 v2, 48, v132
	v_lshlrev_b32_e32 v4, 6, v150
	v_and_b32_e32 v5, 32, v5
	v_bitop3_b32 v4, v4, v5, v2 bitop3:0x36
	v_readlane_b32 s12, v254, 7
	v_lshlrev_b32_e32 v11, 6, v132
	s_add_i32 s2, s2, s3
	v_add_u32_e32 v7, s12, v4
	s_movk_i32 s12, 0x3c0
	v_and_or_b32 v2, v11, s12, v2
	v_xad_u32 v5, v2, v5, 0
	v_lshlrev_b32_e32 v2, 14, v18
	v_and_b32_e32 v2, 0xffff8000, v2
	v_ashrrev_i32_e32 v139, 6, v138
	v_lshl_add_u32 v2, v19, 11, v2
	v_and_b32_e32 v14, 1, v18
	s_ashr_i32 s3, s2, 31
	v_and_b32_e32 v140, 3, v139
	s_waitcnt vmcnt(6)
	s_add_i32 s15, 0, 0x10000
	v_lshlrev_b32_e32 v10, 13, v21
	v_lshl_or_b32 v2, v14, 6, v2
	s_lshl_b64 s[2:3], s[2:3], 11
	v_lshlrev_b32_e32 v3, 12, v140
	v_add_u32_e32 v6, s15, v4
	v_add_u32_e32 v8, s22, v4
	v_add_u32_e32 v9, s13, v4
	v_add_u32_e32 v4, 0, v4
	v_or_b32_e32 v11, 0x800, v10
	v_or_b32_e32 v12, 0x1000, v10
	v_or_b32_e32 v13, 0x1800, v10
	v_lshl_add_u32 v130, v20, 1, v2
	s_add_u32 s12, s10, s2
	v_mov_b32_e32 v2, 0
	s_mov_b64 s[26:27], 0x80
	v_lshlrev_b32_e32 v142, 6, v21
	v_mov_b32_e32 v131, v1
	s_addc_u32 s13, s11, s3
	s_mov_b32 s22, -2
	v_add_u32_e32 v157, v6, v3
	v_add_u32_e32 v146, v4, v10
	v_add_u32_e32 v145, v5, v11
	v_add_u32_e32 v144, v5, v12
	v_add_u32_e32 v143, v5, v13
	v_add_u32_e32 v154, v7, v3
	v_add_u32_e32 v148, v8, v3
	v_add_u32_e32 v147, v9, v3
	v_mov_b32_e32 v3, v2
	v_mov_b32_e32 v4, v2
	v_mov_b32_e32 v5, v2
	v_mov_b32_e32 v6, v2
	v_mov_b32_e32 v7, v2
	v_mov_b32_e32 v8, v2
	v_mov_b32_e32 v9, v2
	v_mov_b32_e32 v10, v2
	v_mov_b32_e32 v11, v2
	v_mov_b32_e32 v12, v2
	v_mov_b32_e32 v13, v2
	v_mov_b32_e32 v14, v2
	v_mov_b32_e32 v15, v2
	v_mov_b32_e32 v16, v2
	v_mov_b32_e32 v17, v2
	v_mov_b32_e32 v18, v2
	v_mov_b32_e32 v19, v2
	v_mov_b32_e32 v20, v2
	v_mov_b32_e32 v21, v2
	v_mov_b32_e32 v22, v2
	v_mov_b32_e32 v23, v2
	v_mov_b32_e32 v24, v2
	v_mov_b32_e32 v25, v2
	v_mov_b32_e32 v26, v2
	v_mov_b32_e32 v27, v2
	v_mov_b32_e32 v28, v2
	v_mov_b32_e32 v29, v2
	v_mov_b32_e32 v30, v2
	v_mov_b32_e32 v31, v2
	v_mov_b32_e32 v32, v2
	v_mov_b32_e32 v33, v2
	v_mov_b32_e32 v34, v2
	v_mov_b32_e32 v35, v2
	v_mov_b32_e32 v36, v2
	v_mov_b32_e32 v37, v2
	v_mov_b32_e32 v38, v2
	v_mov_b32_e32 v39, v2
	v_mov_b32_e32 v40, v2
	v_mov_b32_e32 v41, v2
	v_mov_b32_e32 v42, v2
	v_mov_b32_e32 v43, v2
	v_mov_b32_e32 v44, v2
	v_mov_b32_e32 v45, v2
	v_mov_b32_e32 v46, v2
	v_mov_b32_e32 v47, v2
	v_mov_b32_e32 v48, v2
	v_mov_b32_e32 v49, v2
	v_mov_b32_e32 v50, v2
	v_mov_b32_e32 v51, v2
	v_mov_b32_e32 v52, v2
	v_mov_b32_e32 v53, v2
	v_mov_b32_e32 v54, v2
	v_mov_b32_e32 v55, v2
	v_mov_b32_e32 v56, v2
	v_mov_b32_e32 v57, v2
	v_mov_b32_e32 v58, v2
	v_mov_b32_e32 v59, v2
	v_mov_b32_e32 v60, v2
	v_mov_b32_e32 v61, v2
	v_mov_b32_e32 v62, v2
	v_mov_b32_e32 v63, v2
	v_mov_b32_e32 v64, v2
	v_mov_b32_e32 v65, v2
	v_mov_b32_e32 v66, v2
	v_mov_b32_e32 v67, v2
	v_mov_b32_e32 v68, v2
	v_mov_b32_e32 v69, v2
	v_mov_b32_e32 v70, v2
	v_mov_b32_e32 v71, v2
	v_mov_b32_e32 v72, v2
	v_mov_b32_e32 v73, v2
	v_mov_b32_e32 v74, v2
	v_mov_b32_e32 v75, v2
	v_mov_b32_e32 v76, v2
	v_mov_b32_e32 v77, v2
	v_mov_b32_e32 v78, v2
	v_mov_b32_e32 v79, v2
	v_mov_b32_e32 v80, v2
	v_mov_b32_e32 v81, v2
	v_mov_b32_e32 v82, v2
	v_mov_b32_e32 v83, v2
	v_mov_b32_e32 v84, v2
	v_mov_b32_e32 v85, v2
	v_mov_b32_e32 v86, v2
	v_mov_b32_e32 v87, v2
	v_mov_b32_e32 v88, v2
	v_mov_b32_e32 v89, v2
	v_mov_b32_e32 v90, v2
	v_mov_b32_e32 v91, v2
	v_mov_b32_e32 v92, v2
	v_mov_b32_e32 v93, v2
	v_mov_b32_e32 v94, v2
	v_mov_b32_e32 v95, v2
	v_mov_b32_e32 v96, v2
	v_mov_b32_e32 v97, v2
	v_mov_b32_e32 v98, v2
	v_mov_b32_e32 v99, v2
	v_mov_b32_e32 v100, v2
	v_mov_b32_e32 v101, v2
	v_mov_b32_e32 v102, v2
	v_mov_b32_e32 v103, v2
	v_mov_b32_e32 v104, v2
	v_mov_b32_e32 v105, v2
	v_mov_b32_e32 v106, v2
	v_mov_b32_e32 v107, v2
	v_mov_b32_e32 v108, v2
	v_mov_b32_e32 v109, v2
	v_mov_b32_e32 v110, v2
	v_mov_b32_e32 v111, v2
	v_mov_b32_e32 v112, v2
	v_mov_b32_e32 v113, v2
	v_mov_b32_e32 v114, v2
	v_mov_b32_e32 v115, v2
	v_mov_b32_e32 v116, v2
	v_mov_b32_e32 v117, v2
	v_mov_b32_e32 v118, v2
	v_mov_b32_e32 v119, v2
	v_mov_b32_e32 v120, v2
	v_mov_b32_e32 v121, v2
	v_mov_b32_e32 v122, v2
	v_mov_b32_e32 v123, v2
	v_mov_b32_e32 v124, v2
	v_mov_b32_e32 v125, v2
	v_mov_b32_e32 v126, v2
	v_mov_b32_e32 v127, v2
	v_mov_b32_e32 v128, v2
	v_mov_b32_e32 v129, v2
	s_mov_b64 s[24:25], 0x8240080
	s_mov_b64 s[34:35], 0x8260080
	s_mov_b64 s[36:37], 0x8200100
	s_mov_b64 s[42:43], 0x8220100
	s_mov_b64 s[44:45], 0x8240100
	s_mov_b64 s[46:47], 0x8260100
	s_mov_b64 s[48:49], 0x8200180
	s_mov_b64 s[50:51], 0x8220180
	s_mov_b64 s[52:53], 0x20100
	s_mov_b64 s[56:57], 0x40100
	s_mov_b64 s[66:67], 0x60100
	s_mov_b64 s[76:77], 0x20180
	s_mov_b64 s[96:97], 0x40180
	s_mov_b64 s[60:61], 0x60180
	s_cmp_ge_u32 s33, 0x100
	s_cbranch_scc0 .Lprio_done_1
	s_setprio 1

; #define GPTR(T, ptr) ((__attribute__((address_space(1))) T*)(ptr))
; __device__ __forceinline__ float frsq(float x) { return __builtin_amdgcn_rsqf(x); }
; __device__ __forceinline__ int ptid_(int wave) { int l_; asm volatile("v_mbcnt_lo_u32_b32 %0, -1, 0\n\tv_mbcnt_hi_u32_b32 %0, -1, %0" : "=v"(l_)); return (wave << 6) | l_; }
; #define STAGE_B(P, br, kt) do { const char* _gb = (const char*)(Bt + ((long)(br) * K + (long)(kt) * BK)); \
;     __builtin_amdgcn_global_load_lds((const unsigned*)(_gb + bofl0), (unsigned*)((char*)(P) + gtid_ * 16), 16, 0, 0); \
;     __builtin_amdgcn_global_load_lds((const unsigned*)(_gb + (long)K * 128 + bofl0), (unsigned*)((char*)(P) + gtid_ * 16 + 8192), 16, 0, 0); } while (0)
; #define BAR __builtin_amdgcn_s_barrier()
; template <int EPI>
; __device__ __forceinline__ void gemm_tile(const GemmArgs& g, int brow, int bcol, int parity, bool first, bool nvalid, int nbrow, int nbcol) {
;     ...
;   int gtid_ = ptid_(g.tid);
;   const int wid = gtid_ >> 6, lane = gtid_ & 63, wr = wid >> 2, wc = wid & 3, fr = lane & 15, fq = lane >> 4;
;   unsigned aofl0, bofl0;
;   { int _r, _c; stage_rc(gtid_ * 16, _r, _c); aofl0 = (unsigned)(_r * lda + _c) * 2u; bofl0 = (unsigned)(_r * K + _c) * 2u; }
;   f32x4 acc[2][2][4][2] = {};
;   bf16x8 At[4][2], B0[2][2], B1[2][2];
;   const int nt = K / BK;
;   float* rstd_s = (float*)(smem + 153600) + (parity & 1) * 256;
;   if (first) {
;     WAIT_V(0);
;     __syncthreads();
;     STAGE_B(SB(0, 0), bcol, 0); STAGE_A(SA(0, 0), brow, 0);
;     STAGE_B(SB(0, 1), bcol + HALF, 0); STAGE_A(SA(0, 1), brow + HALF, 0);
;   }
;   f32x4 ra0, ra1, ra2, ra3;
;   if constexpr (EPI != EPI_RES) {
;     if (gtid_ < 256) {
;       const __attribute__((address_space(1))) f32x4* pp = GPTR(const f32x4, g.rowss + (long)(brow + gtid_) * 16);
;       ra0 = pp[0]; ra1 = pp[1]; ra2 = pp[2]; ra3 = pp[3];
;     }
;   }
;   if (wr == 1) BAR;
;   if (first) { WAIT_V(4); } else { WAIT_V(0); }
;   BAR;
;   if constexpr (EPI != EPI_RES) {
;     if (gtid_ < 256) {
;       float s = ((ra0[0] + ra0[1]) + (ra0[2] + ra0[3])) + ((ra1[0] + ra1[1]) + (ra1[2] + ra1[3])) + ((ra2[0] + ra2[1]) + (ra2[2] + ra2[3])) + ((ra3[0] + ra3[1]) + (ra3[2] + ra3[3]));
;       rstd_s[gtid_] = frsq(s * (1.0f / 1024.0f) + 1e-6f);
;     }
;   }
;   STAGE_B(SB(1, 0), bcol, 1); STAGE_A(SA(1, 0), brow, 1); STAGE_B(SB(1, 1), bcol + HALF, 1);
;   WAIT_V(6); BAR;
.LBB0_165:
	s_or_b64 exec, exec, s[12:13]
	s_ashr_i32 s41, s40, 31
	s_lshl_b64 s[12:13], s[40:41], 11
	s_add_u32 s0, s19, s12
	v_readlane_b32 s25, v254, 8
	s_addc_u32 s1, s21, s13
	s_waitcnt vmcnt(0)
	v_lshl_add_u64 v[2:3], s[0:1], 0, v[0:1]
	v_add_u32_e32 v150, s25, v142
	s_mov_b64 s[26:27], 0x80
	v_readfirstlane_b32 s0, v150
	v_add_u32_e32 v151, 0x2000, v150
	v_lshl_add_u64 v[4:5], v[2:3], 0, s[26:27]
	s_mov_b32 m0, s0
	v_readfirstlane_b32 s0, v151
	s_ashr_i32 s39, s38, 31
	global_load_lds_dwordx4 v[4:5], off
	s_mov_b32 m0, s0
	s_lshl_b64 s[0:1], s[38:39], 11
	s_mov_b64 s[42:43], 0x20080
	s_add_u32 s0, s80, s0
	v_lshl_add_u64 v[2:3], v[2:3], 0, s[42:43]
	s_addc_u32 s1, s81, s1
	v_add_u32_e32 v152, 0x8000, v137
	global_load_lds_dwordx4 v[2:3], off
	v_lshl_add_u64 v[2:3], s[0:1], 0, v[0:1]
	v_readfirstlane_b32 s0, v152
	v_add_u32_e32 v153, 0xa000, v137
	v_lshl_add_u64 v[4:5], v[2:3], 0, s[26:27]
	s_mov_b32 m0, s0
	v_readfirstlane_b32 s0, v153
	global_load_lds_dwordx4 v[4:5], off
	s_mov_b32 m0, s0
	s_or_b32 s0, s40, 0x80
	s_ashr_i32 s1, s0, 31
	s_lshl_b64 s[0:1], s[0:1], 11
	s_add_u32 s0, s19, s0
	v_lshl_add_u64 v[2:3], v[2:3], 0, s[42:43]
	s_addc_u32 s1, s21, s1
	global_load_lds_dwordx4 v[2:3], off
	v_lshl_add_u64 v[2:3], s[0:1], 0, v[0:1]
	v_readlane_b32 s1, v254, 9
	v_lshl_add_u64 v[4:5], v[2:3], 0, s[26:27]
	v_lshl_add_u64 v[2:3], v[2:3], 0, s[42:43]
	v_add_u32_e32 v155, s1, v142
	v_add_u32_e32 v156, 0x2000, v155
	v_readfirstlane_b32 s0, v155
	s_mov_b32 m0, s0
	v_readfirstlane_b32 s0, v156
	global_load_lds_dwordx4 v[4:5], off
	s_mov_b32 m0, s0
	v_and_b32_e32 v139, 15, v132
	global_load_lds_dwordx4 v[2:3], off
	v_lshlrev_b32_e32 v5, 2, v132
	v_and_b32_e32 v2, 48, v132
	v_lshlrev_b32_e32 v4, 6, v139
	v_and_b32_e32 v5, 32, v5
	v_bitop3_b32 v4, v4, v5, v2 bitop3:0x36
	v_readlane_b32 s0, v254, 7
	v_lshlrev_b32_e32 v11, 6, v132
	v_add_u32_e32 v9, s1, v4
	v_add_u32_e32 v7, s0, v4
	s_movk_i32 s0, 0x3c0
	v_and_or_b32 v2, v11, s0, v2
	s_add_i32 s0, s2, s3
	v_xad_u32 v5, v2, v5, 0
	v_lshlrev_b32_e32 v2, 14, v18
	s_ashr_i32 s1, s0, 31
	s_add_i32 s15, 0, 0x10000
	v_and_b32_e32 v2, 0xffff8000, v2
	s_lshl_b64 s[0:1], s[0:1], 11
	v_ashrrev_i32_e32 v140, 6, v138
	v_lshl_add_u32 v2, v19, 11, v2
	v_and_b32_e32 v14, 1, v18
	s_add_u32 s0, s10, s0
	v_and_b32_e32 v141, 3, v140
	s_waitcnt vmcnt(6)
	v_lshlrev_b32_e32 v10, 13, v21
	v_lshl_or_b32 v2, v14, 6, v2
	s_addc_u32 s1, s11, s1
	v_lshlrev_b32_e32 v3, 12, v141
	v_add_u32_e32 v6, s15, v4
	v_add_u32_e32 v8, s25, v4
	v_add_u32_e32 v4, 0, v4
	v_or_b32_e32 v11, 0x800, v10
	v_or_b32_e32 v12, 0x1000, v10
	v_or_b32_e32 v13, 0x1800, v10
	v_lshl_add_u32 v130, v20, 1, v2
	s_add_u32 s12, s22, s12
	v_mov_b32_e32 v2, 0
	v_lshlrev_b32_e32 v143, 6, v21
	v_mov_b32_e32 v131, v1
	s_addc_u32 s13, s23, s13
	s_mov_b32 s25, -2
	v_add_u32_e32 v157, v6, v3
	v_add_u32_e32 v147, v4, v10
	v_add_u32_e32 v146, v5, v11
	v_add_u32_e32 v145, v5, v12
	v_add_u32_e32 v144, v5, v13
	v_add_u32_e32 v154, v7, v3
	v_add_u32_e32 v149, v8, v3
	v_add_u32_e32 v148, v9, v3
	v_mov_b32_e32 v3, v2
	v_mov_b32_e32 v4, v2
	v_mov_b32_e32 v5, v2
	v_mov_b32_e32 v6, v2
	v_mov_b32_e32 v7, v2
	v_mov_b32_e32 v8, v2
	v_mov_b32_e32 v9, v2
	v_mov_b32_e32 v10, v2
	v_mov_b32_e32 v11, v2
	v_mov_b32_e32 v12, v2
	v_mov_b32_e32 v13, v2
	v_mov_b32_e32 v14, v2
	v_mov_b32_e32 v15, v2
	v_mov_b32_e32 v16, v2
	v_mov_b32_e32 v17, v2
	v_mov_b32_e32 v18, v2
	v_mov_b32_e32 v19, v2
	v_mov_b32_e32 v20, v2
	v_mov_b32_e32 v21, v2
	v_mov_b32_e32 v22, v2
	v_mov_b32_e32 v23, v2
	v_mov_b32_e32 v24, v2
	v_mov_b32_e32 v25, v2
	v_mov_b32_e32 v26, v2
	v_mov_b32_e32 v27, v2
	v_mov_b32_e32 v28, v2
	v_mov_b32_e32 v29, v2
	v_mov_b32_e32 v30, v2
	v_mov_b32_e32 v31, v2
	v_mov_b32_e32 v32, v2
	v_mov_b32_e32 v33, v2
	v_mov_b32_e32 v34, v2
	v_mov_b32_e32 v35, v2
	v_mov_b32_e32 v36, v2
	v_mov_b32_e32 v37, v2
	v_mov_b32_e32 v38, v2
	v_mov_b32_e32 v39, v2
	v_mov_b32_e32 v40, v2
	v_mov_b32_e32 v41, v2
	v_mov_b32_e32 v42, v2
	v_mov_b32_e32 v43, v2
	v_mov_b32_e32 v44, v2
	v_mov_b32_e32 v45, v2
	v_mov_b32_e32 v46, v2
	v_mov_b32_e32 v47, v2
	v_mov_b32_e32 v48, v2
	v_mov_b32_e32 v49, v2
	v_mov_b32_e32 v50, v2
	v_mov_b32_e32 v51, v2
	v_mov_b32_e32 v52, v2
	v_mov_b32_e32 v53, v2
	v_mov_b32_e32 v54, v2
	v_mov_b32_e32 v55, v2
	v_mov_b32_e32 v56, v2
	v_mov_b32_e32 v57, v2
	v_mov_b32_e32 v58, v2
	v_mov_b32_e32 v59, v2
	v_mov_b32_e32 v60, v2
	v_mov_b32_e32 v61, v2
	v_mov_b32_e32 v62, v2
	v_mov_b32_e32 v63, v2
	v_mov_b32_e32 v64, v2
	v_mov_b32_e32 v65, v2
	v_mov_b32_e32 v66, v2
	v_mov_b32_e32 v67, v2
	v_mov_b32_e32 v68, v2
	v_mov_b32_e32 v69, v2
	v_mov_b32_e32 v70, v2
	v_mov_b32_e32 v71, v2
	v_mov_b32_e32 v72, v2
	v_mov_b32_e32 v73, v2
	v_mov_b32_e32 v74, v2
	v_mov_b32_e32 v75, v2
	v_mov_b32_e32 v76, v2
	v_mov_b32_e32 v77, v2
	v_mov_b32_e32 v78, v2
	v_mov_b32_e32 v79, v2
	v_mov_b32_e32 v80, v2
	v_mov_b32_e32 v81, v2
	v_mov_b32_e32 v82, v2
	v_mov_b32_e32 v83, v2
	v_mov_b32_e32 v84, v2
	v_mov_b32_e32 v85, v2
	v_mov_b32_e32 v86, v2
	v_mov_b32_e32 v87, v2
	v_mov_b32_e32 v88, v2
	v_mov_b32_e32 v89, v2
	v_mov_b32_e32 v90, v2
	v_mov_b32_e32 v91, v2
	v_mov_b32_e32 v92, v2
	v_mov_b32_e32 v93, v2
	v_mov_b32_e32 v94, v2
	v_mov_b32_e32 v95, v2
	v_mov_b32_e32 v96, v2
	v_mov_b32_e32 v97, v2
	v_mov_b32_e32 v98, v2
	v_mov_b32_e32 v99, v2
	v_mov_b32_e32 v100, v2
	v_mov_b32_e32 v101, v2
	v_mov_b32_e32 v102, v2
	v_mov_b32_e32 v103, v2
	v_mov_b32_e32 v104, v2
	v_mov_b32_e32 v105, v2
	v_mov_b32_e32 v106, v2
	v_mov_b32_e32 v107, v2
	v_mov_b32_e32 v108, v2
	v_mov_b32_e32 v109, v2
	v_mov_b32_e32 v110, v2
	v_mov_b32_e32 v111, v2
	v_mov_b32_e32 v112, v2
	v_mov_b32_e32 v113, v2
	v_mov_b32_e32 v114, v2
	v_mov_b32_e32 v115, v2
	v_mov_b32_e32 v116, v2
	v_mov_b32_e32 v117, v2
	v_mov_b32_e32 v118, v2
	v_mov_b32_e32 v119, v2
	v_mov_b32_e32 v120, v2
	v_mov_b32_e32 v121, v2
	v_mov_b32_e32 v122, v2
	v_mov_b32_e32 v123, v2
	v_mov_b32_e32 v124, v2
	v_mov_b32_e32 v125, v2
	v_mov_b32_e32 v126, v2
	v_mov_b32_e32 v127, v2
	v_mov_b32_e32 v128, v2
	v_mov_b32_e32 v129, v2
	s_mov_b64 s[26:27], 0x8240080
	s_mov_b64 s[42:43], 0x8260080
	s_mov_b64 s[44:45], 0x8200100
	s_mov_b64 s[46:47], 0x8220100
	s_mov_b64 s[48:49], 0x8240100
	s_mov_b64 s[50:51], 0x8260100
	s_mov_b64 s[52:53], 0x8200180
	s_mov_b64 s[56:57], 0x8220180
	s_mov_b64 s[66:67], 0x20100
	s_mov_b64 s[76:77], 0x40100
	s_mov_b64 s[96:97], 0x60100
	s_mov_b64 vcc, 0x20180
	s_mov_b64 s[60:61], 0x40180
	s_mov_b64 s[94:95], 0x60180
	s_cmp_ge_u32 s33, 0x100
	s_cbranch_scc0 .Lprio_done_2
	s_setprio 1

; #define GPTR(T, ptr) ((__attribute__((address_space(1))) T*)(ptr))
; __device__ __forceinline__ float frsq(float x) { return __builtin_amdgcn_rsqf(x); }
; __device__ __forceinline__ int ptid_(int wave) { int l_; asm volatile("v_mbcnt_lo_u32_b32 %0, -1, 0\n\tv_mbcnt_hi_u32_b32 %0, -1, %0" : "=v"(l_)); return (wave << 6) | l_; }
; #define STAGE_B(P, br, kt) do { const char* _gb = (const char*)(Bt + ((long)(br) * K + (long)(kt) * BK)); \
;     __builtin_amdgcn_global_load_lds((const unsigned*)(_gb + bofl0), (unsigned*)((char*)(P) + gtid_ * 16), 16, 0, 0); \
;     __builtin_amdgcn_global_load_lds((const unsigned*)(_gb + (long)K * 128 + bofl0), (unsigned*)((char*)(P) + gtid_ * 16 + 8192), 16, 0, 0); } while (0)
; #define BAR __builtin_amdgcn_s_barrier()
; template <int EPI>
; __device__ __forceinline__ void gemm_tile(const GemmArgs& g, int brow, int bcol, int parity, bool first, bool nvalid, int nbrow, int nbcol) {
;     ...
;   int gtid_ = ptid_(g.tid);
;   const int wid = gtid_ >> 6, lane = gtid_ & 63, wr = wid >> 2, wc = wid & 3, fr = lane & 15, fq = lane >> 4;
;   unsigned aofl0, bofl0;
;   { int _r, _c; stage_rc(gtid_ * 16, _r, _c); aofl0 = (unsigned)(_r * lda + _c) * 2u; bofl0 = (unsigned)(_r * K + _c) * 2u; }
;   f32x4 acc[2][2][4][2] = {};
;   bf16x8 At[4][2], B0[2][2], B1[2][2];
;   const int nt = K / BK;
;   float* rstd_s = (float*)(smem + 153600) + (parity & 1) * 256;
;   if (first) {
;     WAIT_V(0);
;     __syncthreads();
;     STAGE_B(SB(0, 0), bcol, 0); STAGE_A(SA(0, 0), brow, 0);
;     STAGE_B(SB(0, 1), bcol + HALF, 0); STAGE_A(SA(0, 1), brow + HALF, 0);
;   }
;   f32x4 ra0, ra1, ra2, ra3;
;   if constexpr (EPI != EPI_RES) {
;     if (gtid_ < 256) {
;       const __attribute__((address_space(1))) f32x4* pp = GPTR(const f32x4, g.rowss + (long)(brow + gtid_) * 16);
;       ra0 = pp[0]; ra1 = pp[1]; ra2 = pp[2]; ra3 = pp[3];
;     }
;   }
;   if (wr == 1) BAR;
;   if (first) { WAIT_V(4); } else { WAIT_V(0); }
;   BAR;
;   if constexpr (EPI != EPI_RES) {
;     if (gtid_ < 256) {
;       float s = ((ra0[0] + ra0[1]) + (ra0[2] + ra0[3])) + ((ra1[0] + ra1[1]) + (ra1[2] + ra1[3])) + ((ra2[0] + ra2[1]) + (ra2[2] + ra2[3])) + ((ra3[0] + ra3[1]) + (ra3[2] + ra3[3]));
;       rstd_s[gtid_] = frsq(s * (1.0f / 1024.0f) + 1e-6f);
;     }
;   }
;   STAGE_B(SB(1, 0), bcol, 1); STAGE_A(SA(1, 0), brow, 1); STAGE_B(SB(1, 1), bcol + HALF, 1);
;   WAIT_V(6); BAR;
.LBB0_190:
	s_ashr_i32 s21, s20, 31
	s_lshl_b64 s[2:3], s[18:19], 1
	s_add_u32 s2, s48, s2
	v_readlane_b32 s18, v254, 8
	s_addc_u32 s3, s49, s3
	v_lshl_add_u64 v[6:7], s[2:3], 0, v[0:1]
	v_add_u32_e32 v152, s18, v146
	s_mov_b64 s[22:23], 0x80
	v_readfirstlane_b32 s12, v152
	s_add_u32 s2, s2, s50
	v_lshl_add_u64 v[6:7], v[6:7], 0, s[22:23]
	s_mov_b32 m0, s12
	s_addc_u32 s3, s3, 0
	v_add_u32_e32 v153, 0x2000, v152
	s_barrier
	global_load_lds_dwordx4 v[6:7], off
	v_lshl_add_u64 v[6:7], s[2:3], 0, v[0:1]
	v_readfirstlane_b32 s2, v153
	s_mov_b32 m0, s2
	s_lshl_b64 s[2:3], s[14:15], 1
	s_add_u32 s25, s47, s2
	s_addc_u32 s39, s46, s3
	s_add_u32 s2, s25, s96
	v_lshl_add_u64 v[6:7], v[6:7], 0, s[22:23]
	s_addc_u32 s3, s39, 0
	v_mov_b32_e32 v131, v1
	v_add_u32_e32 v155, 0x8000, v140
	global_load_lds_dwordx4 v[6:7], off
	v_lshl_add_u64 v[6:7], s[2:3], 0, v[130:131]
	v_readfirstlane_b32 s12, v155
	s_add_u32 s2, s2, s53
	v_lshl_add_u64 v[6:7], v[6:7], 0, s[22:23]
	s_mov_b32 m0, s12
	s_addc_u32 s3, s3, 0
	v_add_u32_e32 v156, 0xa000, v140
	global_load_lds_dwordx4 v[6:7], off
	v_lshl_add_u64 v[6:7], s[2:3], 0, v[130:131]
	v_readfirstlane_b32 s2, v156
	s_mov_b32 m0, s2
	s_or_b32 s2, s20, 0x80
	s_mul_hi_i32 s3, s2, s34
	s_mul_i32 s2, s2, s34
	s_lshl_b64 s[2:3], s[2:3], 1
	s_add_u32 s2, s48, s2
	v_readlane_b32 s14, v254, 9
	v_lshl_add_u64 v[6:7], v[6:7], 0, s[22:23]
	s_addc_u32 s3, s49, s3
	v_add_u32_e32 v157, s14, v146
	global_load_lds_dwordx4 v[6:7], off
	v_lshl_add_u64 v[6:7], s[2:3], 0, v[0:1]
	v_readfirstlane_b32 s12, v157
	s_add_u32 s2, s2, s50
	v_lshl_add_u64 v[6:7], v[6:7], 0, s[22:23]
	s_mov_b32 m0, s12
	s_addc_u32 s3, s3, 0
	v_add_u32_e32 v158, 0x2000, v157
	global_load_lds_dwordx4 v[6:7], off
	v_lshl_add_u64 v[6:7], s[2:3], 0, v[0:1]
	v_readfirstlane_b32 s2, v158
	v_lshl_add_u64 v[6:7], v[6:7], 0, s[22:23]
	s_mov_b32 m0, s2
	s_or_b32 s2, s38, 0x80
	global_load_lds_dwordx4 v[6:7], off
	v_and_b32_e32 v142, 15, v137
	v_lshlrev_b32_e32 v144, 2, v137
	s_mul_hi_i32 s3, s2, s37
	s_mul_i32 s2, s2, s37
	v_and_b32_e32 v7, 48, v137
	v_lshlrev_b32_e32 v8, 6, v142
	v_and_b32_e32 v9, 32, v144
	s_add_i32 s40, 0, 0x10000
	s_lshl_b64 s[12:13], s[2:3], 1
	v_bitop3_b32 v8, v8, v9, v7 bitop3:0x36
	s_add_u32 s41, s47, s12
	v_readlane_b32 s2, v254, 7
	s_addc_u32 s44, s46, s13
	v_lshlrev_b32_e32 v14, 6, v137
	v_add_u32_e32 v11, s2, v8
	s_movk_i32 s2, 0x3c0
	s_mul_i32 s3, s74, s20
	v_add_u32_e32 v13, s14, v8
	v_and_or_b32 v7, v14, s2, v7
	s_mul_hi_i32 s2, s74, s20
	s_add_u32 s14, s31, s3
	s_addc_u32 s15, s73, s2
	s_lshl_b64 s[2:3], s[20:21], 1
	v_add_u32_e32 v12, s18, v8
	s_add_u32 s18, s2, 0x80
	s_addc_u32 s19, s3, 0
	s_mul_i32 s19, s34, s19
	s_mul_hi_u32 s22, s34, s18
	s_add_i32 s22, s22, s19
	s_mul_i32 s18, s34, s18
	s_add_u32 s18, s31, s18
	s_addc_u32 s19, s73, s22
	s_add_u32 s20, s20, 0x80
	s_addc_u32 s21, s21, 0
	s_mul_i32 s21, s74, s21
	s_mul_hi_u32 s22, s74, s20
	s_add_i32 s22, s22, s21
	s_mul_i32 s20, s74, s20
	s_add_u32 s20, s31, s20
	s_addc_u32 s21, s73, s22
	s_add_u32 s2, s2, 0x180
	s_addc_u32 s3, s3, 0
	v_ashrrev_i32_e32 v143, 6, v141
	s_mul_i32 s3, s34, s3
	s_mul_hi_u32 s22, s34, s2
	v_and_b32_e32 v138, 3, v143
	s_waitcnt vmcnt(6)
	v_lshlrev_b32_e32 v145, 6, v5
	v_lshlrev_b32_e32 v5, 13, v5
	v_add_u32_e32 v2, v4, v2
	s_add_i32 s3, s22, s3
	s_mul_i32 s2, s34, s2
	v_lshlrev_b32_e32 v6, 12, v138
	v_add_u32_e32 v10, s40, v8
	v_add_u32_e32 v8, 0, v8
	v_xad_u32 v7, v7, v9, 0
	v_or_b32_e32 v9, 0x800, v5
	v_or_b32_e32 v14, 0x1000, v5
	v_or_b32_e32 v15, 0x1800, v5
	v_add_lshl_u32 v132, v2, v3, 1
	s_add_u32 s22, s31, s2
	v_mov_b32_e32 v2, 0
	v_mov_b32_e32 v133, v1
	s_addc_u32 s23, s73, s3
	s_mov_b32 s45, 0
	s_movk_i32 s61, 0xc0
	v_add_u32_e32 v160, v10, v6
	v_add_u32_e32 v150, v8, v5
	v_add_u32_e32 v149, v7, v9
	v_add_u32_e32 v148, v7, v14
	v_add_u32_e32 v147, v7, v15
	v_add_u32_e32 v159, v11, v6
	v_add_u32_e32 v154, v12, v6
	v_add_u32_e32 v151, v13, v6
	v_mov_b32_e32 v3, v2
	v_mov_b32_e32 v4, v2
	v_mov_b32_e32 v5, v2
	v_mov_b32_e32 v6, v2
	v_mov_b32_e32 v7, v2
	v_mov_b32_e32 v8, v2
	v_mov_b32_e32 v9, v2
	v_mov_b32_e32 v10, v2
	v_mov_b32_e32 v11, v2
	v_mov_b32_e32 v12, v2
	v_mov_b32_e32 v13, v2
	v_mov_b32_e32 v14, v2
	v_mov_b32_e32 v15, v2
	v_mov_b32_e32 v16, v2
	v_mov_b32_e32 v17, v2
	v_mov_b32_e32 v18, v2
	v_mov_b32_e32 v19, v2
	v_mov_b32_e32 v20, v2
	v_mov_b32_e32 v21, v2
	v_mov_b32_e32 v22, v2
	v_mov_b32_e32 v23, v2
	v_mov_b32_e32 v24, v2
	v_mov_b32_e32 v25, v2
	v_mov_b32_e32 v26, v2
	v_mov_b32_e32 v27, v2
	v_mov_b32_e32 v28, v2
	v_mov_b32_e32 v29, v2
	v_mov_b32_e32 v30, v2
	v_mov_b32_e32 v31, v2
	v_mov_b32_e32 v32, v2
	v_mov_b32_e32 v33, v2
	v_mov_b32_e32 v34, v2
	v_mov_b32_e32 v35, v2
	v_mov_b32_e32 v36, v2
	v_mov_b32_e32 v37, v2
	v_mov_b32_e32 v38, v2
	v_mov_b32_e32 v39, v2
	v_mov_b32_e32 v40, v2
	v_mov_b32_e32 v41, v2
	v_mov_b32_e32 v42, v2
	v_mov_b32_e32 v43, v2
	v_mov_b32_e32 v44, v2
	v_mov_b32_e32 v45, v2
	v_mov_b32_e32 v46, v2
	v_mov_b32_e32 v47, v2
	v_mov_b32_e32 v48, v2
	v_mov_b32_e32 v49, v2
	v_mov_b32_e32 v50, v2
	v_mov_b32_e32 v51, v2
	v_mov_b32_e32 v52, v2
	v_mov_b32_e32 v53, v2
	v_mov_b32_e32 v54, v2
	v_mov_b32_e32 v55, v2
	v_mov_b32_e32 v56, v2
	v_mov_b32_e32 v57, v2
	v_mov_b32_e32 v58, v2
	v_mov_b32_e32 v59, v2
	v_mov_b32_e32 v60, v2
	v_mov_b32_e32 v61, v2
	v_mov_b32_e32 v62, v2
	v_mov_b32_e32 v63, v2
	v_mov_b32_e32 v64, v2
	v_mov_b32_e32 v65, v2
	v_mov_b32_e32 v66, v2
	v_mov_b32_e32 v67, v2
	v_mov_b32_e32 v68, v2
	v_mov_b32_e32 v69, v2
	v_mov_b32_e32 v70, v2
	v_mov_b32_e32 v71, v2
	v_mov_b32_e32 v72, v2
	v_mov_b32_e32 v73, v2
	v_mov_b32_e32 v74, v2
	v_mov_b32_e32 v75, v2
	v_mov_b32_e32 v76, v2
	v_mov_b32_e32 v77, v2
	v_mov_b32_e32 v78, v2
	v_mov_b32_e32 v79, v2
	v_mov_b32_e32 v80, v2
	v_mov_b32_e32 v81, v2
	v_mov_b32_e32 v82, v2
	v_mov_b32_e32 v83, v2
	v_mov_b32_e32 v84, v2
	v_mov_b32_e32 v85, v2
	v_mov_b32_e32 v86, v2
	v_mov_b32_e32 v87, v2
	v_mov_b32_e32 v88, v2
	v_mov_b32_e32 v89, v2
	v_mov_b32_e32 v90, v2
	v_mov_b32_e32 v91, v2
	v_mov_b32_e32 v92, v2
	v_mov_b32_e32 v93, v2
	v_mov_b32_e32 v94, v2
	v_mov_b32_e32 v95, v2
	v_mov_b32_e32 v96, v2
	v_mov_b32_e32 v97, v2
	v_mov_b32_e32 v98, v2
	v_mov_b32_e32 v99, v2
	v_mov_b32_e32 v100, v2
	v_mov_b32_e32 v101, v2
	v_mov_b32_e32 v102, v2
	v_mov_b32_e32 v103, v2
	v_mov_b32_e32 v104, v2
	v_mov_b32_e32 v105, v2
	v_mov_b32_e32 v106, v2
	v_mov_b32_e32 v107, v2
	v_mov_b32_e32 v108, v2
	v_mov_b32_e32 v109, v2
	v_mov_b32_e32 v110, v2
	v_mov_b32_e32 v111, v2
	v_mov_b32_e32 v112, v2
	v_mov_b32_e32 v113, v2
	v_mov_b32_e32 v114, v2
	v_mov_b32_e32 v115, v2
	v_mov_b32_e32 v116, v2
	v_mov_b32_e32 v117, v2
	v_mov_b32_e32 v118, v2
	v_mov_b32_e32 v119, v2
	v_mov_b32_e32 v120, v2
	v_mov_b32_e32 v121, v2
	v_mov_b32_e32 v122, v2
	v_mov_b32_e32 v123, v2
	v_mov_b32_e32 v124, v2
	v_mov_b32_e32 v125, v2
	v_mov_b32_e32 v126, v2
	v_mov_b32_e32 v127, v2
	v_mov_b32_e32 v128, v2
	v_mov_b32_e32 v129, v2
	s_cmp_ge_u32 s33, 0x100
	s_cbranch_scc0 .Lprio_done_3
	s_setprio 1

; #define GPTR(T, ptr) ((__attribute__((address_space(1))) T*)(ptr))
; __device__ __forceinline__ float frsq(float x) { return __builtin_amdgcn_rsqf(x); }
; __device__ __forceinline__ int ptid_(int wave) { int l_; asm volatile("v_mbcnt_lo_u32_b32 %0, -1, 0\n\tv_mbcnt_hi_u32_b32 %0, -1, %0" : "=v"(l_)); return (wave << 6) | l_; }
; #define STAGE_B(P, br, kt) do { const char* _gb = (const char*)(Bt + ((long)(br) * K + (long)(kt) * BK)); \
;     __builtin_amdgcn_global_load_lds((const unsigned*)(_gb + bofl0), (unsigned*)((char*)(P) + gtid_ * 16), 16, 0, 0); \
;     __builtin_amdgcn_global_load_lds((const unsigned*)(_gb + (long)K * 128 + bofl0), (unsigned*)((char*)(P) + gtid_ * 16 + 8192), 16, 0, 0); } while (0)
; #define BAR __builtin_amdgcn_s_barrier()
; template <int EPI>
; __device__ __forceinline__ void gemm_tile(const GemmArgs& g, int brow, int bcol, int parity, bool first, bool nvalid, int nbrow, int nbcol) {
;     ...
;   int gtid_ = ptid_(g.tid);
;   const int wid = gtid_ >> 6, lane = gtid_ & 63, wr = wid >> 2, wc = wid & 3, fr = lane & 15, fq = lane >> 4;
;   unsigned aofl0, bofl0;
;   { int _r, _c; stage_rc(gtid_ * 16, _r, _c); aofl0 = (unsigned)(_r * lda + _c) * 2u; bofl0 = (unsigned)(_r * K + _c) * 2u; }
;   f32x4 acc[2][2][4][2] = {};
;   bf16x8 At[4][2], B0[2][2], B1[2][2];
;   const int nt = K / BK;
;   float* rstd_s = (float*)(smem + 153600) + (parity & 1) * 256;
;   if (first) {
;     WAIT_V(0);
;     __syncthreads();
;     STAGE_B(SB(0, 0), bcol, 0); STAGE_A(SA(0, 0), brow, 0);
;     STAGE_B(SB(0, 1), bcol + HALF, 0); STAGE_A(SA(0, 1), brow + HALF, 0);
;   }
;   f32x4 ra0, ra1, ra2, ra3;
;   if constexpr (EPI != EPI_RES) {
;     if (gtid_ < 256) {
;       const __attribute__((address_space(1))) f32x4* pp = GPTR(const f32x4, g.rowss + (long)(brow + gtid_) * 16);
;       ra0 = pp[0]; ra1 = pp[1]; ra2 = pp[2]; ra3 = pp[3];
;     }
;   }
;   if (wr == 1) BAR;
;   if (first) { WAIT_V(4); } else { WAIT_V(0); }
;   BAR;
;   if constexpr (EPI != EPI_RES) {
;     if (gtid_ < 256) {
;       float s = ((ra0[0] + ra0[1]) + (ra0[2] + ra0[3])) + ((ra1[0] + ra1[1]) + (ra1[2] + ra1[3])) + ((ra2[0] + ra2[1]) + (ra2[2] + ra2[3])) + ((ra3[0] + ra3[1]) + (ra3[2] + ra3[3]));
;       rstd_s[gtid_] = frsq(s * (1.0f / 1024.0f) + 1e-6f);
;     }
;   }
;   STAGE_B(SB(1, 0), bcol, 1); STAGE_A(SA(1, 0), brow, 1); STAGE_B(SB(1, 1), bcol + HALF, 1);
;   WAIT_V(6); BAR;
.LBB0_639:
	s_or_b64 exec, exec, s[0:1]
	s_ashr_i32 s13, s12, 31
	s_lshl_b64 s[0:1], s[12:13], 11
	s_add_u32 s0, s70, s0
	v_readlane_b32 s15, v255, 0
	v_readlane_b32 s23, v254, 8
	s_addc_u32 s1, s15, s1
	s_ashr_i32 s41, s40, 31
	v_add_u32_e32 v150, s23, v142
	s_waitcnt vmcnt(0)
	v_lshl_add_u64 v[2:3], s[0:1], 0, v[0:1]
	s_mov_b64 s[36:37], 0x80
	v_readfirstlane_b32 s13, v150
	v_add_u32_e32 v151, 0x2000, v150
	s_lshl_b64 s[24:25], s[40:41], 11
	v_lshl_add_u64 v[4:5], v[2:3], 0, s[36:37]
	s_mov_b32 m0, s13
	s_mov_b64 s[38:39], 0x20080
	v_readfirstlane_b32 s13, v151
	s_add_u32 s24, s80, s24
	global_load_lds_dwordx4 v[4:5], off
	v_lshl_add_u64 v[2:3], v[2:3], 0, s[38:39]
	s_mov_b32 m0, s13
	s_addc_u32 s25, s81, s25
	v_add_u32_e32 v152, 0x8000, v137
	global_load_lds_dwordx4 v[2:3], off
	v_lshl_add_u64 v[2:3], s[24:25], 0, v[0:1]
	v_readfirstlane_b32 s13, v152
	v_add_u32_e32 v153, 0xa000, v137
	v_lshl_add_u64 v[4:5], v[2:3], 0, s[36:37]
	s_mov_b32 m0, s13
	v_readfirstlane_b32 s13, v153
	s_bitset1_b32 s12, 7
	global_load_lds_dwordx4 v[4:5], off
	s_mov_b32 m0, s13
	s_ashr_i32 s13, s12, 31
	s_lshl_b64 s[12:13], s[12:13], 11
	s_add_u32 s12, s70, s12
	v_lshl_add_u64 v[2:3], v[2:3], 0, s[38:39]
	s_addc_u32 s13, s15, s13
	global_load_lds_dwordx4 v[2:3], off
	v_lshl_add_u64 v[2:3], s[12:13], 0, v[0:1]
	v_readlane_b32 s13, v254, 9
	v_lshl_add_u64 v[4:5], v[2:3], 0, s[36:37]
	v_lshl_add_u64 v[2:3], v[2:3], 0, s[38:39]
	v_add_u32_e32 v155, s13, v142
	v_add_u32_e32 v156, 0x2000, v155
	v_readfirstlane_b32 s12, v155
	s_mov_b32 m0, s12
	v_readfirstlane_b32 s12, v156
	global_load_lds_dwordx4 v[4:5], off
	s_mov_b32 m0, s12
	v_and_b32_e32 v139, 15, v132
	global_load_lds_dwordx4 v[2:3], off
	v_lshlrev_b32_e32 v5, 2, v132
	v_and_b32_e32 v2, 48, v132
	v_lshlrev_b32_e32 v4, 6, v139
	v_and_b32_e32 v5, 32, v5
	v_bitop3_b32 v4, v4, v5, v2 bitop3:0x36
	v_readlane_b32 s12, v254, 7
	v_lshlrev_b32_e32 v11, 6, v132
	s_add_i32 s2, s2, s3
	v_add_u32_e32 v7, s12, v4
	s_movk_i32 s12, 0x3c0
	v_and_or_b32 v2, v11, s12, v2
	v_xad_u32 v5, v2, v5, 0
	v_lshlrev_b32_e32 v2, 14, v18
	v_and_b32_e32 v2, 0xffff8000, v2
	v_ashrrev_i32_e32 v140, 6, v138
	v_lshl_add_u32 v2, v19, 11, v2
	v_and_b32_e32 v14, 1, v18
	s_ashr_i32 s3, s2, 31
	v_and_b32_e32 v141, 3, v140
	s_waitcnt vmcnt(6)
	s_add_i32 s15, 0, 0x10000
	v_lshlrev_b32_e32 v10, 13, v21
	v_lshl_or_b32 v2, v14, 6, v2
	s_lshl_b64 s[2:3], s[2:3], 11
	v_lshlrev_b32_e32 v3, 12, v141
	v_add_u32_e32 v6, s15, v4
	v_add_u32_e32 v8, s23, v4
	v_add_u32_e32 v9, s13, v4
	v_add_u32_e32 v4, 0, v4
	v_or_b32_e32 v11, 0x800, v10
	v_or_b32_e32 v12, 0x1000, v10
	v_or_b32_e32 v13, 0x1800, v10
	v_lshl_add_u32 v130, v20, 1, v2
	s_add_u32 s12, s10, s2
	v_mov_b32_e32 v2, 0
	v_lshlrev_b32_e32 v143, 6, v21
	v_mov_b32_e32 v131, v1
	s_addc_u32 s13, s11, s3
	s_mov_b32 s23, -2
	v_add_u32_e32 v157, v6, v3
	v_add_u32_e32 v147, v4, v10
	v_add_u32_e32 v146, v5, v11
	v_add_u32_e32 v145, v5, v12
	v_add_u32_e32 v144, v5, v13
	v_add_u32_e32 v154, v7, v3
	v_add_u32_e32 v149, v8, v3
	v_add_u32_e32 v148, v9, v3
	v_mov_b32_e32 v3, v2
	v_mov_b32_e32 v4, v2
	v_mov_b32_e32 v5, v2
	v_mov_b32_e32 v6, v2
	v_mov_b32_e32 v7, v2
	v_mov_b32_e32 v8, v2
	v_mov_b32_e32 v9, v2
	v_mov_b32_e32 v10, v2
	v_mov_b32_e32 v11, v2
	v_mov_b32_e32 v12, v2
	v_mov_b32_e32 v13, v2
	v_mov_b32_e32 v14, v2
	v_mov_b32_e32 v15, v2
	v_mov_b32_e32 v16, v2
	v_mov_b32_e32 v17, v2
	v_mov_b32_e32 v18, v2
	v_mov_b32_e32 v19, v2
	v_mov_b32_e32 v20, v2
	v_mov_b32_e32 v21, v2
	v_mov_b32_e32 v22, v2
	v_mov_b32_e32 v23, v2
	v_mov_b32_e32 v24, v2
	v_mov_b32_e32 v25, v2
	v_mov_b32_e32 v26, v2
	v_mov_b32_e32 v27, v2
	v_mov_b32_e32 v28, v2
	v_mov_b32_e32 v29, v2
	v_mov_b32_e32 v30, v2
	v_mov_b32_e32 v31, v2
	v_mov_b32_e32 v32, v2
	v_mov_b32_e32 v33, v2
	v_mov_b32_e32 v34, v2
	v_mov_b32_e32 v35, v2
	v_mov_b32_e32 v36, v2
	v_mov_b32_e32 v37, v2
	v_mov_b32_e32 v38, v2
	v_mov_b32_e32 v39, v2
	v_mov_b32_e32 v40, v2
	v_mov_b32_e32 v41, v2
	v_mov_b32_e32 v42, v2
	v_mov_b32_e32 v43, v2
	v_mov_b32_e32 v44, v2
	v_mov_b32_e32 v45, v2
	v_mov_b32_e32 v46, v2
	v_mov_b32_e32 v47, v2
	v_mov_b32_e32 v48, v2
	v_mov_b32_e32 v49, v2
	v_mov_b32_e32 v50, v2
	v_mov_b32_e32 v51, v2
	v_mov_b32_e32 v52, v2
	v_mov_b32_e32 v53, v2
	v_mov_b32_e32 v54, v2
	v_mov_b32_e32 v55, v2
	v_mov_b32_e32 v56, v2
	v_mov_b32_e32 v57, v2
	v_mov_b32_e32 v58, v2
	v_mov_b32_e32 v59, v2
	v_mov_b32_e32 v60, v2
	v_mov_b32_e32 v61, v2
	v_mov_b32_e32 v62, v2
	v_mov_b32_e32 v63, v2
	v_mov_b32_e32 v64, v2
	v_mov_b32_e32 v65, v2
	v_mov_b32_e32 v66, v2
	v_mov_b32_e32 v67, v2
	v_mov_b32_e32 v68, v2
	v_mov_b32_e32 v69, v2
	v_mov_b32_e32 v70, v2
	v_mov_b32_e32 v71, v2
	v_mov_b32_e32 v72, v2
	v_mov_b32_e32 v73, v2
	v_mov_b32_e32 v74, v2
	v_mov_b32_e32 v75, v2
	v_mov_b32_e32 v76, v2
	v_mov_b32_e32 v77, v2
	v_mov_b32_e32 v78, v2
	v_mov_b32_e32 v79, v2
	v_mov_b32_e32 v80, v2
	v_mov_b32_e32 v81, v2
	v_mov_b32_e32 v82, v2
	v_mov_b32_e32 v83, v2
	v_mov_b32_e32 v84, v2
	v_mov_b32_e32 v85, v2
	v_mov_b32_e32 v86, v2
	v_mov_b32_e32 v87, v2
	v_mov_b32_e32 v88, v2
	v_mov_b32_e32 v89, v2
	v_mov_b32_e32 v90, v2
	v_mov_b32_e32 v91, v2
	v_mov_b32_e32 v92, v2
	v_mov_b32_e32 v93, v2
	v_mov_b32_e32 v94, v2
	v_mov_b32_e32 v95, v2
	v_mov_b32_e32 v96, v2
	v_mov_b32_e32 v97, v2
	v_mov_b32_e32 v98, v2
	v_mov_b32_e32 v99, v2
	v_mov_b32_e32 v100, v2
	v_mov_b32_e32 v101, v2
	v_mov_b32_e32 v102, v2
	v_mov_b32_e32 v103, v2
	v_mov_b32_e32 v104, v2
	v_mov_b32_e32 v105, v2
	v_mov_b32_e32 v106, v2
	v_mov_b32_e32 v107, v2
	v_mov_b32_e32 v108, v2
	v_mov_b32_e32 v109, v2
	v_mov_b32_e32 v110, v2
	v_mov_b32_e32 v111, v2
	v_mov_b32_e32 v112, v2
	v_mov_b32_e32 v113, v2
	v_mov_b32_e32 v114, v2
	v_mov_b32_e32 v115, v2
	v_mov_b32_e32 v116, v2
	v_mov_b32_e32 v117, v2
	v_mov_b32_e32 v118, v2
	v_mov_b32_e32 v119, v2
	v_mov_b32_e32 v120, v2
	v_mov_b32_e32 v121, v2
	v_mov_b32_e32 v122, v2
	v_mov_b32_e32 v123, v2
	v_mov_b32_e32 v124, v2
	v_mov_b32_e32 v125, v2
	v_mov_b32_e32 v126, v2
	v_mov_b32_e32 v127, v2
	v_mov_b32_e32 v128, v2
	v_mov_b32_e32 v129, v2
	s_mov_b64 s[24:25], 0x8240080
	s_mov_b64 s[36:37], 0x8260080
	s_mov_b64 s[38:39], 0x8200100
	s_mov_b64 s[42:43], 0x8220100
	s_mov_b64 s[44:45], 0x8240100
	s_mov_b64 s[46:47], 0x8260100
	s_mov_b64 s[48:49], 0x8200180
	s_mov_b64 s[50:51], 0x8220180
	s_mov_b64 s[66:67], 0x20100
	s_mov_b64 s[76:77], 0x40100
	s_mov_b64 s[96:97], 0x60100
	s_mov_b64 vcc, 0x20180
	s_mov_b64 s[60:61], 0x40180
	s_mov_b64 s[94:95], 0x60180
	s_cmp_ge_u32 s33, 0x100
	s_cbranch_scc0 .Lprio_done_4
	s_setprio 1
